# attention unit: static s_setprio 1 for waves 0-3 instead of 4-7
# baseline (speedup 1.0000x reference)
.LBB0_1984:
	s_or_b64 exec, exec, s[0:1]
	v_readlane_b32 s0, v253, 25
	s_waitcnt vmcnt(0) lgkmcnt(0)
	s_barrier
	v_mov_b32_e32 v0, s0
	ds_read_b32 v0, v0
	s_waitcnt lgkmcnt(0)
	s_barrier
	v_readfirstlane_b32 s0, v0
	s_cmp_lt_i32 s0, 0
	s_cbranch_scc1 .LBB0_2003
	s_getreg_b32 s1, hwreg(HW_REG_HW_ID, 0, 7)
	s_and_b32 s1, s1, 63
	s_lshl_b32 s1, s1, 2
	s_add_i32 s1, s1, 0x22240
	v_mov_b32_e32 v0, s1
	ds_read_b32 v0, v0
	v_mbcnt_lo_u32_b32 v34, -1, 0
	v_mbcnt_hi_u32_b32 v34, -1, v34
	s_bfe_u32 s27, s0, 0x50001
	s_and_b32 s45, s0, 1
	s_lshr_b32 s1, s0, 15
	s_waitcnt lgkmcnt(0)
	v_lshl_or_b32 v4, v0, 6, v34
	s_lshl_b32 s0, s0, 7
	v_readfirstlane_b32 s47, v4
	s_ashr_i32 s44, s47, 6
	s_cmp_lt_u32 s44, 4
	s_cbranch_scc0 .Lprio_skip
	s_setprio 1
